# grid seams: waiting workgroups poll the cross-XCC release generation directly (per-XCC re-release hop removed), on top of arrival-time L1 invalidates; P11 exchange invalidate issued with its write-bac
# speedup vs baseline: 1.0331x; 1.0047x over previous
; __device__ __forceinline__ unsigned xb_ld(unsigned* p)              { return __hip_atomic_load(p, __ATOMIC_RELAXED, __HIP_MEMORY_SCOPE_AGENT); }
; __device__ __forceinline__ unsigned xb_add(unsigned* p, unsigned v) { return __hip_atomic_fetch_add(p, v, __ATOMIC_RELAXED, __HIP_MEMORY_SCOPE_AGENT); }
; #define XB_SPIN(cond, bar) do { unsigned _sp = 0; while (cond) { __builtin_amdgcn_s_sleep(1); \
;     if ((++_sp & 255u) == 0u) { if (xb_ld(&(bar)[XB_TMO])) break; if (_sp > XB_SPIN_CAP) { atomicAdd(&(bar)[XB_TMO], 1u); break; } } } } while (0)
; __device__ __forceinline__ void xcd_barrier(const XcdBarrier& b) {
;     ...
;         const unsigned old = xb_add(&bar[XB_XSUB(b.x)], 1u);
;         const unsigned gen = old / nloc;
;         if (old + 1u == (gen + 1u) * nloc) {
;             __builtin_amdgcn_fence(__ATOMIC_RELEASE, "agent");
;             asm volatile("s_waitcnt vmcnt(0)" ::: "memory");
;             const unsigned og = xb_add(&bar[XB_TOP], 1u);
;             const unsigned tg = og / nx;
;             if (og + 1u == (tg + 1u) * nx) xb_add(&bar[XB_TOPGEN], 1u);
;             else XB_SPIN(xb_ld(&bar[XB_TOPGEN]) == tg, bar);
;             __builtin_amdgcn_fence(__ATOMIC_ACQUIRE, "agent");
;             xb_add(&bar[XB_XGEN(b.x)], 1u);
;             asm volatile("s_waitcnt vmcnt(0)" ::: "memory");
;         } else {
;             XB_SPIN(xb_ld(&bar[XB_XGEN(b.x)]) == gen, bar);
;             __builtin_amdgcn_fence(__ATOMIC_ACQUIRE, "agent");
.LBB0_207:
	s_or_b64 exec, exec, s[14:15]
	v_cvt_f32_u32_e32 v5, v3
	s_waitcnt vmcnt(0)
	v_readfirstlane_b32 s0, v4
	v_sub_u32_e32 v4, 0, v3
	v_rcp_iflag_f32_e32 v5, v5
	v_add_u32_e32 v6, s0, v2
	v_mul_f32_e32 v5, 0x4f7ffffe, v5
	v_cvt_u32_f32_e32 v5, v5
	v_mul_lo_u32 v2, v4, v5
	v_mul_hi_u32 v2, v5, v2
	v_add_u32_e32 v2, v5, v2
	v_mul_hi_u32 v2, v6, v2
	v_mul_lo_u32 v4, v2, v3
	v_sub_u32_e32 v4, v6, v4
	v_add_u32_e32 v5, 1, v2
	v_cmp_ge_u32_e32 vcc, v4, v3
	s_nop 1
	v_cndmask_b32_e32 v2, v2, v5, vcc
	v_sub_u32_e32 v5, v4, v3
	v_cndmask_b32_e32 v4, v4, v5, vcc
	v_add_u32_e32 v5, 1, v2
	v_cmp_ge_u32_e32 vcc, v4, v3
	v_add_u32_e32 v4, 1, v6
	s_nop 0
	v_cndmask_b32_e32 v2, v2, v5, vcc
	v_mul_lo_u32 v5, v3, v2
	v_add_u32_e32 v3, v5, v3
	v_cmp_ne_u32_e32 vcc, v4, v3
	s_and_saveexec_b64 s[0:1], vcc
	s_xor_b64 s[12:13], exec, s[0:1]
	s_cbranch_execz .LBB0_221
	s_waitcnt lgkmcnt(0)
	buffer_inv sc1
	s_add_u32 s18, s26, 0xff03500
	s_addc_u32 s19, s27, 0
	v_mov_b32_e32 v1, 0
	global_load_dword v1, v1, s[18:19] sc1
	s_waitcnt vmcnt(0)
	v_cmp_eq_u32_e32 vcc, v1, v2
	s_and_saveexec_b64 s[14:15], vcc
	s_cbranch_execz .LBB0_220
	s_add_u32 s16, s26, 0xff00200
	s_addc_u32 s17, s27, 0
	s_mov_b32 s0, 1
	s_mov_b64 s[20:21], 0
	v_mov_b32_e32 v1, 0
	s_branch .LBB0_211

; __device__ __forceinline__ unsigned xb_ld(unsigned* p)              { return __hip_atomic_load(p, __ATOMIC_RELAXED, __HIP_MEMORY_SCOPE_AGENT); }
; __device__ __forceinline__ unsigned xb_add(unsigned* p, unsigned v) { return __hip_atomic_fetch_add(p, v, __ATOMIC_RELAXED, __HIP_MEMORY_SCOPE_AGENT); }
; #define XB_SPIN(cond, bar) do { unsigned _sp = 0; while (cond) { __builtin_amdgcn_s_sleep(1); \
;     if ((++_sp & 255u) == 0u) { if (xb_ld(&(bar)[XB_TMO])) break; if (_sp > XB_SPIN_CAP) { atomicAdd(&(bar)[XB_TMO], 1u); break; } } } } while (0)
; __device__ __forceinline__ void xcd_barrier(const XcdBarrier& b) {
;     ...
;             if (og + 1u == (tg + 1u) * nx) xb_add(&bar[XB_TOPGEN], 1u);
;             else XB_SPIN(xb_ld(&bar[XB_TOPGEN]) == tg, bar);
;             __builtin_amdgcn_fence(__ATOMIC_ACQUIRE, "agent");
;             xb_add(&bar[XB_XGEN(b.x)], 1u);
;             asm volatile("s_waitcnt vmcnt(0)" ::: "memory");
.LBB0_238:
	s_or_b64 exec, exec, s[12:13]
	s_mov_b64 s[12:13], exec
	v_mbcnt_lo_u32_b32 v1, s12, 0
	v_mbcnt_hi_u32_b32 v1, s13, v1
	v_cmp_eq_u32_e32 vcc, 0, v1
	s_waitcnt vmcnt(0) lgkmcnt(0)
	s_and_saveexec_b64 s[14:15], vcc
	s_cbranch_execz .LBB0_240
	s_bcnt1_i32_b64 s0, s[12:13]
	v_mov_b32_e32 v1, 0x2000
	v_mov_b32_e32 v2, s0
.LBB0_240:
	s_or_b64 exec, exec, s[14:15]
	s_waitcnt vmcnt(0)

; __device__ __forceinline__ unsigned xb_ld(unsigned* p)              { return __hip_atomic_load(p, __ATOMIC_RELAXED, __HIP_MEMORY_SCOPE_AGENT); }
; __device__ __forceinline__ unsigned xb_add(unsigned* p, unsigned v) { return __hip_atomic_fetch_add(p, v, __ATOMIC_RELAXED, __HIP_MEMORY_SCOPE_AGENT); }
; #define XB_SPIN(cond, bar) do { unsigned _sp = 0; while (cond) { __builtin_amdgcn_s_sleep(1); \
;     if ((++_sp & 255u) == 0u) { if (xb_ld(&(bar)[XB_TMO])) break; if (_sp > XB_SPIN_CAP) { atomicAdd(&(bar)[XB_TMO], 1u); break; } } } } while (0)
; __device__ __forceinline__ void xcd_barrier(const XcdBarrier& b) {
;     ...
;             if (og + 1u == (tg + 1u) * nx) xb_add(&bar[XB_TOPGEN], 1u);
;             else XB_SPIN(xb_ld(&bar[XB_TOPGEN]) == tg, bar);
;             __builtin_amdgcn_fence(__ATOMIC_ACQUIRE, "agent");
;             xb_add(&bar[XB_XGEN(b.x)], 1u);
;             asm volatile("s_waitcnt vmcnt(0)" ::: "memory");
.LBB0_465:
	s_or_b64 exec, exec, s[12:13]
	s_mov_b64 s[12:13], exec
	v_mbcnt_lo_u32_b32 v1, s12, 0
	v_mbcnt_hi_u32_b32 v1, s13, v1
	v_cmp_eq_u32_e32 vcc, 0, v1
	s_waitcnt vmcnt(0)
	s_and_saveexec_b64 s[14:15], vcc
	s_cbranch_execz .LBB0_467
	s_bcnt1_i32_b64 s0, s[12:13]
	v_mov_b32_e32 v1, 0x2000
	v_mov_b32_e32 v2, s0
.LBB0_467:
	s_or_b64 exec, exec, s[14:15]
	s_waitcnt vmcnt(0)

; __device__ __forceinline__ unsigned xb_ld(unsigned* p)              { return __hip_atomic_load(p, __ATOMIC_RELAXED, __HIP_MEMORY_SCOPE_AGENT); }
; __device__ __forceinline__ unsigned xb_add(unsigned* p, unsigned v) { return __hip_atomic_fetch_add(p, v, __ATOMIC_RELAXED, __HIP_MEMORY_SCOPE_AGENT); }
; #define XB_SPIN(cond, bar) do { unsigned _sp = 0; while (cond) { __builtin_amdgcn_s_sleep(1); \
;     if ((++_sp & 255u) == 0u) { if (xb_ld(&(bar)[XB_TMO])) break; if (_sp > XB_SPIN_CAP) { atomicAdd(&(bar)[XB_TMO], 1u); break; } } } } while (0)
; __device__ __forceinline__ void xcd_barrier(const XcdBarrier& b) {
;     ...
;             if (og + 1u == (tg + 1u) * nx) xb_add(&bar[XB_TOPGEN], 1u);
;             else XB_SPIN(xb_ld(&bar[XB_TOPGEN]) == tg, bar);
;             __builtin_amdgcn_fence(__ATOMIC_ACQUIRE, "agent");
;             xb_add(&bar[XB_XGEN(b.x)], 1u);
;             asm volatile("s_waitcnt vmcnt(0)" ::: "memory");
.LBB0_562:
	s_or_b64 exec, exec, s[12:13]
	s_mov_b64 s[12:13], exec
	v_mbcnt_lo_u32_b32 v1, s12, 0
	v_mbcnt_hi_u32_b32 v1, s13, v1
	v_cmp_eq_u32_e32 vcc, 0, v1
	s_waitcnt vmcnt(0)
	s_and_saveexec_b64 s[14:15], vcc
	s_cbranch_execz .LBB0_564
	s_bcnt1_i32_b64 s0, s[12:13]
	v_mov_b32_e32 v1, 0x2000
	v_mov_b32_e32 v2, s0
.LBB0_564:
	s_or_b64 exec, exec, s[14:15]
	s_waitcnt vmcnt(0)

; __device__ __forceinline__ unsigned xb_ld(unsigned* p)              { return __hip_atomic_load(p, __ATOMIC_RELAXED, __HIP_MEMORY_SCOPE_AGENT); }
; __device__ __forceinline__ unsigned xb_add(unsigned* p, unsigned v) { return __hip_atomic_fetch_add(p, v, __ATOMIC_RELAXED, __HIP_MEMORY_SCOPE_AGENT); }
; #define XB_SPIN(cond, bar) do { unsigned _sp = 0; while (cond) { __builtin_amdgcn_s_sleep(1); \
;     if ((++_sp & 255u) == 0u) { if (xb_ld(&(bar)[XB_TMO])) break; if (_sp > XB_SPIN_CAP) { atomicAdd(&(bar)[XB_TMO], 1u); break; } } } } while (0)
; __device__ __forceinline__ void xcd_barrier(const XcdBarrier& b) {
;     ...
;             if (og + 1u == (tg + 1u) * nx) xb_add(&bar[XB_TOPGEN], 1u);
;             else XB_SPIN(xb_ld(&bar[XB_TOPGEN]) == tg, bar);
;             __builtin_amdgcn_fence(__ATOMIC_ACQUIRE, "agent");
;             xb_add(&bar[XB_XGEN(b.x)], 1u);
;             asm volatile("s_waitcnt vmcnt(0)" ::: "memory");
.LBB0_707:
	s_or_b64 exec, exec, s[12:13]
	s_mov_b64 s[12:13], exec
	v_mbcnt_lo_u32_b32 v1, s12, 0
	v_mbcnt_hi_u32_b32 v1, s13, v1
	v_cmp_eq_u32_e32 vcc, 0, v1
	s_waitcnt vmcnt(0)
	s_and_saveexec_b64 s[14:15], vcc
	s_cbranch_execz .LBB0_709
	s_bcnt1_i32_b64 s0, s[12:13]
	v_mov_b32_e32 v1, 0x2000
	v_mov_b32_e32 v2, s0
.LBB0_709:
	s_or_b64 exec, exec, s[14:15]
	s_waitcnt vmcnt(0)

; __device__ __forceinline__ unsigned xb_ld(unsigned* p)              { return __hip_atomic_load(p, __ATOMIC_RELAXED, __HIP_MEMORY_SCOPE_AGENT); }
; __device__ __forceinline__ unsigned xb_add(unsigned* p, unsigned v) { return __hip_atomic_fetch_add(p, v, __ATOMIC_RELAXED, __HIP_MEMORY_SCOPE_AGENT); }
; #define XB_SPIN(cond, bar) do { unsigned _sp = 0; while (cond) { __builtin_amdgcn_s_sleep(1); \
;     if ((++_sp & 255u) == 0u) { if (xb_ld(&(bar)[XB_TMO])) break; if (_sp > XB_SPIN_CAP) { atomicAdd(&(bar)[XB_TMO], 1u); break; } } } } while (0)
; __device__ __forceinline__ void xcd_barrier(const XcdBarrier& b) {
;     ...
;             if (og + 1u == (tg + 1u) * nx) xb_add(&bar[XB_TOPGEN], 1u);
;             else XB_SPIN(xb_ld(&bar[XB_TOPGEN]) == tg, bar);
;             __builtin_amdgcn_fence(__ATOMIC_ACQUIRE, "agent");
;             xb_add(&bar[XB_XGEN(b.x)], 1u);
;             asm volatile("s_waitcnt vmcnt(0)" ::: "memory");
.LBB0_808:
	s_or_b64 exec, exec, s[12:13]
	s_mov_b64 s[12:13], exec
	v_mbcnt_lo_u32_b32 v1, s12, 0
	v_mbcnt_hi_u32_b32 v1, s13, v1
	v_cmp_eq_u32_e32 vcc, 0, v1
	s_waitcnt vmcnt(0)
	s_and_saveexec_b64 s[14:15], vcc
	s_cbranch_execz .LBB0_810
	s_bcnt1_i32_b64 s0, s[12:13]
	v_mov_b32_e32 v1, 0x2000
	v_mov_b32_e32 v2, s0
.LBB0_810:
	s_or_b64 exec, exec, s[14:15]
	s_waitcnt vmcnt(0)

; __device__ __forceinline__ unsigned xb_ld(unsigned* p)              { return __hip_atomic_load(p, __ATOMIC_RELAXED, __HIP_MEMORY_SCOPE_AGENT); }
; __device__ __forceinline__ unsigned xb_add(unsigned* p, unsigned v) { return __hip_atomic_fetch_add(p, v, __ATOMIC_RELAXED, __HIP_MEMORY_SCOPE_AGENT); }
; #define XB_SPIN(cond, bar) do { unsigned _sp = 0; while (cond) { __builtin_amdgcn_s_sleep(1); \
;     if ((++_sp & 255u) == 0u) { if (xb_ld(&(bar)[XB_TMO])) break; if (_sp > XB_SPIN_CAP) { atomicAdd(&(bar)[XB_TMO], 1u); break; } } } } while (0)
; __device__ __forceinline__ void xcd_barrier(const XcdBarrier& b) {
;     ...
;             if (og + 1u == (tg + 1u) * nx) xb_add(&bar[XB_TOPGEN], 1u);
;             else XB_SPIN(xb_ld(&bar[XB_TOPGEN]) == tg, bar);
;             __builtin_amdgcn_fence(__ATOMIC_ACQUIRE, "agent");
;             xb_add(&bar[XB_XGEN(b.x)], 1u);
;             asm volatile("s_waitcnt vmcnt(0)" ::: "memory");
.LBB0_866:
	s_or_b64 exec, exec, s[12:13]
	s_mov_b64 s[12:13], exec
	v_mbcnt_lo_u32_b32 v1, s12, 0
	v_mbcnt_hi_u32_b32 v1, s13, v1
	v_cmp_eq_u32_e32 vcc, 0, v1
	s_waitcnt vmcnt(0)
	s_and_saveexec_b64 s[14:15], vcc
	s_cbranch_execz .LBB0_868
	s_bcnt1_i32_b64 s0, s[12:13]
	v_mov_b32_e32 v1, 0x2000
	v_mov_b32_e32 v2, s0
.LBB0_868:
	s_or_b64 exec, exec, s[14:15]
	s_waitcnt vmcnt(0)

; __device__ __forceinline__ unsigned xb_ld(unsigned* p)              { return __hip_atomic_load(p, __ATOMIC_RELAXED, __HIP_MEMORY_SCOPE_AGENT); }
; __device__ __forceinline__ unsigned xb_add(unsigned* p, unsigned v) { return __hip_atomic_fetch_add(p, v, __ATOMIC_RELAXED, __HIP_MEMORY_SCOPE_AGENT); }
; #define XB_SPIN(cond, bar) do { unsigned _sp = 0; while (cond) { __builtin_amdgcn_s_sleep(1); \
;     if ((++_sp & 255u) == 0u) { if (xb_ld(&(bar)[XB_TMO])) break; if (_sp > XB_SPIN_CAP) { atomicAdd(&(bar)[XB_TMO], 1u); break; } } } } while (0)
; __device__ __forceinline__ void xcd_barrier(const XcdBarrier& b) {
;     ...
;             if (og + 1u == (tg + 1u) * nx) xb_add(&bar[XB_TOPGEN], 1u);
;             else XB_SPIN(xb_ld(&bar[XB_TOPGEN]) == tg, bar);
;             __builtin_amdgcn_fence(__ATOMIC_ACQUIRE, "agent");
;             xb_add(&bar[XB_XGEN(b.x)], 1u);
;             asm volatile("s_waitcnt vmcnt(0)" ::: "memory");
.LBB0_1053:
	s_or_b64 exec, exec, s[12:13]
	s_mov_b64 s[12:13], exec
	v_mbcnt_lo_u32_b32 v1, s12, 0
	v_mbcnt_hi_u32_b32 v1, s13, v1
	v_cmp_eq_u32_e32 vcc, 0, v1
	s_waitcnt vmcnt(0)
	s_and_saveexec_b64 s[14:15], vcc
	s_cbranch_execz .LBB0_1055
	s_bcnt1_i32_b64 s0, s[12:13]
	v_mov_b32_e32 v1, 0x2000
	v_mov_b32_e32 v2, s0
.LBB0_1055:
	s_or_b64 exec, exec, s[14:15]
	s_waitcnt vmcnt(0)

; __device__ __forceinline__ unsigned xb_ld(unsigned* p)              { return __hip_atomic_load(p, __ATOMIC_RELAXED, __HIP_MEMORY_SCOPE_AGENT); }
; __device__ __forceinline__ unsigned xb_add(unsigned* p, unsigned v) { return __hip_atomic_fetch_add(p, v, __ATOMIC_RELAXED, __HIP_MEMORY_SCOPE_AGENT); }
; #define XB_SPIN(cond, bar) do { unsigned _sp = 0; while (cond) { __builtin_amdgcn_s_sleep(1); \
;     if ((++_sp & 255u) == 0u) { if (xb_ld(&(bar)[XB_TMO])) break; if (_sp > XB_SPIN_CAP) { atomicAdd(&(bar)[XB_TMO], 1u); break; } } } } while (0)
; __device__ __forceinline__ void xcd_barrier(const XcdBarrier& b) {
;     ...
;             if (og + 1u == (tg + 1u) * nx) xb_add(&bar[XB_TOPGEN], 1u);
;             else XB_SPIN(xb_ld(&bar[XB_TOPGEN]) == tg, bar);
;             __builtin_amdgcn_fence(__ATOMIC_ACQUIRE, "agent");
;             xb_add(&bar[XB_XGEN(b.x)], 1u);
;             asm volatile("s_waitcnt vmcnt(0)" ::: "memory");
.LBB0_1118:
	s_or_b64 exec, exec, s[12:13]
	s_mov_b64 s[12:13], exec
	v_mbcnt_lo_u32_b32 v1, s12, 0
	v_mbcnt_hi_u32_b32 v1, s13, v1
	v_cmp_eq_u32_e32 vcc, 0, v1
	s_waitcnt vmcnt(0)
	s_and_saveexec_b64 s[14:15], vcc
	s_cbranch_execz .LBB0_1120
	s_bcnt1_i32_b64 s0, s[12:13]
	v_mov_b32_e32 v1, 0x2000
	v_mov_b32_e32 v2, s0
.LBB0_1120:
	s_or_b64 exec, exec, s[14:15]
	s_waitcnt vmcnt(0)

; __device__ __forceinline__ unsigned xb_ld(unsigned* p)              { return __hip_atomic_load(p, __ATOMIC_RELAXED, __HIP_MEMORY_SCOPE_AGENT); }
; __device__ __forceinline__ unsigned xb_add(unsigned* p, unsigned v) { return __hip_atomic_fetch_add(p, v, __ATOMIC_RELAXED, __HIP_MEMORY_SCOPE_AGENT); }
; #define XB_SPIN(cond, bar) do { unsigned _sp = 0; while (cond) { __builtin_amdgcn_s_sleep(1); \
;     if ((++_sp & 255u) == 0u) { if (xb_ld(&(bar)[XB_TMO])) break; if (_sp > XB_SPIN_CAP) { atomicAdd(&(bar)[XB_TMO], 1u); break; } } } } while (0)
; __device__ __forceinline__ void xcd_barrier(const XcdBarrier& b) {
;     ...
;         const unsigned old = xb_add(&bar[XB_XSUB(b.x)], 1u);
;         const unsigned gen = old / nloc;
;         if (old + 1u == (gen + 1u) * nloc) {
;             __builtin_amdgcn_fence(__ATOMIC_RELEASE, "agent");
;             asm volatile("s_waitcnt vmcnt(0)" ::: "memory");
;             const unsigned og = xb_add(&bar[XB_TOP], 1u);
;             const unsigned tg = og / nx;
;             if (og + 1u == (tg + 1u) * nx) xb_add(&bar[XB_TOPGEN], 1u);
;             else XB_SPIN(xb_ld(&bar[XB_TOPGEN]) == tg, bar);
;             __builtin_amdgcn_fence(__ATOMIC_ACQUIRE, "agent");
;             xb_add(&bar[XB_XGEN(b.x)], 1u);
;             asm volatile("s_waitcnt vmcnt(0)" ::: "memory");
;         } else {
;             XB_SPIN(xb_ld(&bar[XB_XGEN(b.x)]) == gen, bar);
;             __builtin_amdgcn_fence(__ATOMIC_ACQUIRE, "agent");
.LBB0_1317:
	s_or_b64 exec, exec, s[12:13]
	v_cvt_f32_u32_e32 v5, v3
	s_waitcnt vmcnt(0)
	v_readfirstlane_b32 s2, v4
	v_sub_u32_e32 v4, 0, v3
	v_rcp_iflag_f32_e32 v5, v5
	v_add_u32_e32 v6, s2, v2
	v_mul_f32_e32 v5, 0x4f7ffffe, v5
	v_cvt_u32_f32_e32 v5, v5
	v_mul_lo_u32 v2, v4, v5
	v_mul_hi_u32 v2, v5, v2
	v_add_u32_e32 v2, v5, v2
	v_mul_hi_u32 v2, v6, v2
	v_mul_lo_u32 v4, v2, v3
	v_sub_u32_e32 v4, v6, v4
	v_add_u32_e32 v5, 1, v2
	v_cmp_ge_u32_e32 vcc, v4, v3
	s_nop 1
	v_cndmask_b32_e32 v2, v2, v5, vcc
	v_sub_u32_e32 v5, v4, v3
	v_cndmask_b32_e32 v4, v4, v5, vcc
	v_add_u32_e32 v5, 1, v2
	v_cmp_ge_u32_e32 vcc, v4, v3
	v_add_u32_e32 v4, 1, v6
	s_nop 0
	v_cndmask_b32_e32 v2, v2, v5, vcc
	v_mul_lo_u32 v5, v3, v2
	v_add_u32_e32 v3, v5, v3
	v_cmp_ne_u32_e32 vcc, v4, v3
	s_and_saveexec_b64 s[2:3], vcc
	s_xor_b64 s[10:11], exec, s[2:3]
	s_cbranch_execz .LBB0_1331
	s_waitcnt lgkmcnt(0)
	buffer_inv sc1
	s_add_u32 s44, s26, 0xff03500
	s_addc_u32 s45, s27, 0
	v_mov_b32_e32 v1, 0
	global_load_dword v1, v1, s[44:45] sc1
	s_waitcnt vmcnt(0)
	v_cmp_eq_u32_e32 vcc, v1, v2
	s_and_saveexec_b64 s[12:13], vcc
	s_cbranch_execz .LBB0_1330
	s_add_u32 s42, s26, 0xff00200
	s_addc_u32 s43, s27, 0
	s_mov_b32 s2, 1
	s_mov_b64 s[46:47], 0
	v_mov_b32_e32 v1, 0
	s_branch .LBB0_1321

; __device__ __forceinline__ unsigned xb_ld(unsigned* p)              { return __hip_atomic_load(p, __ATOMIC_RELAXED, __HIP_MEMORY_SCOPE_AGENT); }
; __device__ __forceinline__ unsigned xb_add(unsigned* p, unsigned v) { return __hip_atomic_fetch_add(p, v, __ATOMIC_RELAXED, __HIP_MEMORY_SCOPE_AGENT); }
; #define XB_SPIN(cond, bar) do { unsigned _sp = 0; while (cond) { __builtin_amdgcn_s_sleep(1); \
;     if ((++_sp & 255u) == 0u) { if (xb_ld(&(bar)[XB_TMO])) break; if (_sp > XB_SPIN_CAP) { atomicAdd(&(bar)[XB_TMO], 1u); break; } } } } while (0)
; __device__ __forceinline__ void xcd_barrier(const XcdBarrier& b) {
;     ...
;             if (og + 1u == (tg + 1u) * nx) xb_add(&bar[XB_TOPGEN], 1u);
;             else XB_SPIN(xb_ld(&bar[XB_TOPGEN]) == tg, bar);
;             __builtin_amdgcn_fence(__ATOMIC_ACQUIRE, "agent");
;             xb_add(&bar[XB_XGEN(b.x)], 1u);
;             asm volatile("s_waitcnt vmcnt(0)" ::: "memory");
.LBB0_1348:
	s_or_b64 exec, exec, s[10:11]
	s_mov_b64 s[10:11], exec
	v_mbcnt_lo_u32_b32 v1, s10, 0
	v_mbcnt_hi_u32_b32 v1, s11, v1
	v_cmp_eq_u32_e32 vcc, 0, v1
	s_waitcnt vmcnt(0)
	s_and_saveexec_b64 s[12:13], vcc
	s_cbranch_execz .LBB0_1350
	s_bcnt1_i32_b64 s2, s[10:11]
	v_mov_b32_e32 v1, 0x2000
	v_mov_b32_e32 v2, s2
.LBB0_1350:
	s_or_b64 exec, exec, s[12:13]
	s_waitcnt vmcnt(0)

; __device__ __forceinline__ unsigned xb_ld(unsigned* p)              { return __hip_atomic_load(p, __ATOMIC_RELAXED, __HIP_MEMORY_SCOPE_AGENT); }
; __device__ __forceinline__ unsigned xb_add(unsigned* p, unsigned v) { return __hip_atomic_fetch_add(p, v, __ATOMIC_RELAXED, __HIP_MEMORY_SCOPE_AGENT); }
; #define XB_SPIN(cond, bar) do { unsigned _sp = 0; while (cond) { __builtin_amdgcn_s_sleep(1); \
;     if ((++_sp & 255u) == 0u) { if (xb_ld(&(bar)[XB_TMO])) break; if (_sp > XB_SPIN_CAP) { atomicAdd(&(bar)[XB_TMO], 1u); break; } } } } while (0)
; __device__ __forceinline__ void xcd_barrier(const XcdBarrier& b) {
;     ...
;         const unsigned old = xb_add(&bar[XB_XSUB(b.x)], 1u);
;         const unsigned gen = old / nloc;
;         if (old + 1u == (gen + 1u) * nloc) {
;             __builtin_amdgcn_fence(__ATOMIC_RELEASE, "agent");
;             asm volatile("s_waitcnt vmcnt(0)" ::: "memory");
;             const unsigned og = xb_add(&bar[XB_TOP], 1u);
;             const unsigned tg = og / nx;
;             if (og + 1u == (tg + 1u) * nx) xb_add(&bar[XB_TOPGEN], 1u);
;             else XB_SPIN(xb_ld(&bar[XB_TOPGEN]) == tg, bar);
;             __builtin_amdgcn_fence(__ATOMIC_ACQUIRE, "agent");
;             xb_add(&bar[XB_XGEN(b.x)], 1u);
;             asm volatile("s_waitcnt vmcnt(0)" ::: "memory");
;         } else {
;             XB_SPIN(xb_ld(&bar[XB_XGEN(b.x)]) == gen, bar);
;             __builtin_amdgcn_fence(__ATOMIC_ACQUIRE, "agent");
.LBB0_1552:
	s_or_b64 exec, exec, s[12:13]
	v_cvt_f32_u32_e32 v5, v3
	s_waitcnt vmcnt(0)
	v_readfirstlane_b32 s2, v4
	v_sub_u32_e32 v4, 0, v3
	v_rcp_iflag_f32_e32 v5, v5
	v_add_u32_e32 v6, s2, v2
	v_mul_f32_e32 v5, 0x4f7ffffe, v5
	v_cvt_u32_f32_e32 v5, v5
	v_mul_lo_u32 v2, v4, v5
	v_mul_hi_u32 v2, v5, v2
	v_add_u32_e32 v2, v5, v2
	v_mul_hi_u32 v2, v6, v2
	v_mul_lo_u32 v4, v2, v3
	v_sub_u32_e32 v4, v6, v4
	v_add_u32_e32 v5, 1, v2
	v_cmp_ge_u32_e32 vcc, v4, v3
	s_nop 1
	v_cndmask_b32_e32 v2, v2, v5, vcc
	v_sub_u32_e32 v5, v4, v3
	v_cndmask_b32_e32 v4, v4, v5, vcc
	v_add_u32_e32 v5, 1, v2
	v_cmp_ge_u32_e32 vcc, v4, v3
	v_add_u32_e32 v4, 1, v6
	s_nop 0
	v_cndmask_b32_e32 v2, v2, v5, vcc
	v_mul_lo_u32 v5, v3, v2
	v_add_u32_e32 v3, v5, v3
	v_cmp_ne_u32_e32 vcc, v4, v3
	s_and_saveexec_b64 s[2:3], vcc
	s_xor_b64 s[10:11], exec, s[2:3]
	s_cbranch_execz .LBB0_1566
	s_waitcnt lgkmcnt(0)
	buffer_inv sc1
	s_add_u32 s16, s26, 0xff03500
	s_addc_u32 s17, s27, 0
	v_mov_b32_e32 v1, 0
	global_load_dword v1, v1, s[16:17] sc1
	s_waitcnt vmcnt(0)
	v_cmp_eq_u32_e32 vcc, v1, v2
	s_and_saveexec_b64 s[12:13], vcc
	s_cbranch_execz .LBB0_1565
	s_add_u32 s14, s26, 0xff00200
	s_addc_u32 s15, s27, 0
	s_mov_b32 s2, 1
	s_mov_b64 s[18:19], 0
	v_mov_b32_e32 v1, 0
	s_branch .LBB0_1556

; __device__ __forceinline__ unsigned xb_ld(unsigned* p)              { return __hip_atomic_load(p, __ATOMIC_RELAXED, __HIP_MEMORY_SCOPE_AGENT); }
; __device__ __forceinline__ unsigned xb_add(unsigned* p, unsigned v) { return __hip_atomic_fetch_add(p, v, __ATOMIC_RELAXED, __HIP_MEMORY_SCOPE_AGENT); }
; #define XB_SPIN(cond, bar) do { unsigned _sp = 0; while (cond) { __builtin_amdgcn_s_sleep(1); \
;     if ((++_sp & 255u) == 0u) { if (xb_ld(&(bar)[XB_TMO])) break; if (_sp > XB_SPIN_CAP) { atomicAdd(&(bar)[XB_TMO], 1u); break; } } } } while (0)
; __device__ __forceinline__ void xcd_barrier(const XcdBarrier& b) {
;     ...
;             if (og + 1u == (tg + 1u) * nx) xb_add(&bar[XB_TOPGEN], 1u);
;             else XB_SPIN(xb_ld(&bar[XB_TOPGEN]) == tg, bar);
;             __builtin_amdgcn_fence(__ATOMIC_ACQUIRE, "agent");
;             xb_add(&bar[XB_XGEN(b.x)], 1u);
;             asm volatile("s_waitcnt vmcnt(0)" ::: "memory");
.LBB0_1583:
	s_or_b64 exec, exec, s[10:11]
	s_mov_b64 s[10:11], exec
	v_mbcnt_lo_u32_b32 v1, s10, 0
	v_mbcnt_hi_u32_b32 v1, s11, v1
	v_cmp_eq_u32_e32 vcc, 0, v1
	s_waitcnt vmcnt(0)
	s_and_saveexec_b64 s[12:13], vcc
	s_cbranch_execz .LBB0_1585
	s_bcnt1_i32_b64 s2, s[10:11]
	v_mov_b32_e32 v1, 0x2000
	v_mov_b32_e32 v2, s2
.LBB0_1585:
	s_or_b64 exec, exec, s[12:13]
	s_waitcnt vmcnt(0)

; __device__ __forceinline__ unsigned xb_ld(unsigned* p)              { return __hip_atomic_load(p, __ATOMIC_RELAXED, __HIP_MEMORY_SCOPE_AGENT); }
; __device__ __forceinline__ unsigned xb_add(unsigned* p, unsigned v) { return __hip_atomic_fetch_add(p, v, __ATOMIC_RELAXED, __HIP_MEMORY_SCOPE_AGENT); }
; #define XB_SPIN(cond, bar) do { unsigned _sp = 0; while (cond) { __builtin_amdgcn_s_sleep(1); \
;     if ((++_sp & 255u) == 0u) { if (xb_ld(&(bar)[XB_TMO])) break; if (_sp > XB_SPIN_CAP) { atomicAdd(&(bar)[XB_TMO], 1u); break; } } } } while (0)
; __device__ __forceinline__ void xcd_barrier(const XcdBarrier& b) {
;     ...
;             if (og + 1u == (tg + 1u) * nx) xb_add(&bar[XB_TOPGEN], 1u);
;             else XB_SPIN(xb_ld(&bar[XB_TOPGEN]) == tg, bar);
;             __builtin_amdgcn_fence(__ATOMIC_ACQUIRE, "agent");
;             xb_add(&bar[XB_XGEN(b.x)], 1u);
;             asm volatile("s_waitcnt vmcnt(0)" ::: "memory");
.LBB0_1680:
	s_or_b64 exec, exec, s[10:11]
	s_mov_b64 s[10:11], exec
	v_mbcnt_lo_u32_b32 v1, s10, 0
	v_mbcnt_hi_u32_b32 v1, s11, v1
	v_cmp_eq_u32_e32 vcc, 0, v1
	s_waitcnt vmcnt(0)
	s_and_saveexec_b64 s[12:13], vcc
	s_cbranch_execz .LBB0_1682
	s_bcnt1_i32_b64 s2, s[10:11]
	v_mov_b32_e32 v1, 0x2000
	v_mov_b32_e32 v2, s2
.LBB0_1682:
	s_or_b64 exec, exec, s[12:13]
	s_waitcnt vmcnt(0)

;     __device__ __forceinline__ void fused(const f32x4 (&acc_)[2][2][4][2], const Unit& u, int wr, int wc, int fr, int fq, LAS unsigned char*, int, int) const {
;     ...
;         asm volatile("s_waitcnt vmcnt(0)" ::: "memory");
;         __syncthreads();
;         if (threadIdx.x == 0) {
;             __builtin_amdgcn_fence(__ATOMIC_RELEASE, "agent");
;             asm volatile("s_waitcnt vmcnt(0)" ::: "memory");
;             unsigned* c = cnt + 64 * u.pm;
;             (void)__hip_atomic_fetch_add(c, 1u, __ATOMIC_RELAXED, __HIP_MEMORY_SCOPE_AGENT);
.LBB0_1782:
	s_or_b64 exec, exec, s[6:7]
	s_waitcnt vmcnt(0)
	s_waitcnt lgkmcnt(0)
	s_barrier
	s_and_saveexec_b64 s[0:1], s[72:73]
	s_cbranch_execz .LBB0_1794
	s_lshl_b32 s2, s8, 6
	s_ashr_i32 s3, s2, 31
	s_lshl_b64 s[2:3], s[2:3], 2
	s_mov_b64 s[10:11], exec
	s_add_u32 s2, s26, s2
	buffer_inv sc1
	buffer_wbl2 sc1
	s_waitcnt vmcnt(0)
	s_waitcnt vmcnt(0)
	s_addc_u32 s3, s27, s3
	v_mbcnt_lo_u32_b32 v0, s10, 0
	s_add_u32 s6, s2, 0xff04000
	v_mbcnt_hi_u32_b32 v0, s11, v0
	s_addc_u32 s7, s3, 0
	v_cmp_eq_u32_e32 vcc, 0, v0
	s_and_saveexec_b64 s[8:9], vcc
	s_cbranch_execz .LBB0_1785
	s_bcnt1_i32_b64 s2, s[10:11]
	v_mov_b32_e32 v0, 0
	v_mov_b32_e32 v1, s2
	global_atomic_add v0, v1, s[6:7]

;     __device__ __forceinline__ void fused(const f32x4 (&acc_)[2][2][4][2], const Unit& u, int wr, int wc, int fr, int fq, LAS unsigned char*, int, int) const {
;     ...
;             while (__hip_atomic_load(c, __ATOMIC_RELAXED, __HIP_MEMORY_SCOPE_AGENT) < 4u) { __builtin_amdgcn_s_sleep(1); if (++sp > (1u << 22)) break; }
;             __builtin_amdgcn_fence(__ATOMIC_ACQUIRE, "agent");
;             asm volatile("s_waitcnt vmcnt(0)" ::: "memory");
;         }
;         __syncthreads();
;         f32x4 g0[2], g1[2];
; #pragma unroll
;         for (int bj = 0; bj < 2; ++bj) { g0[bj] = *(const f32x4*)(gfin + col0 + bj * 128); g1[bj] = *(const f32x4*)(gfin + col0 + bj * 128 + 4); }
; #pragma unroll
;         for (int ai = 0; ai < 2; ++ai)
; #pragma unroll
;             for (int m = 0; m < 4; ++m) {
;                 const int row = row0 + ai * 128 + m * 16; const float rs = row_rstd_q(ssq, row, fq);
; #pragma unroll
;                 for (int bj = 0; bj < 2; ++bj) {
;                     const size_t off = (size_t)row * D_ + col0 + bj * 128;
;                     *(f32x4*)(out + off) = acc[ai][bj][m][0] * rs * g0[bj]; *(f32x4*)(out + off + 4) = acc[ai][bj][m][1] * rs * g1[bj];
.LBB0_1787:
	global_load_dword v1, v0, s[6:7] sc1
	s_mov_b64 s[8:9], -1
	s_waitcnt vmcnt(0)
	v_cmp_lt_u32_e32 vcc, 3, v1
	s_cbranch_vccnz .LBB0_1786
	s_sleep 1
	global_load_dword v1, v0, s[6:7] sc1
	s_waitcnt vmcnt(0)
	v_cmp_gt_u32_e32 vcc, 4, v1
	s_cbranch_vccz .LBB0_1786
	s_sleep 1
	global_load_dword v1, v0, s[6:7] sc1
	s_waitcnt vmcnt(0)
	v_cmp_gt_u32_e32 vcc, 4, v1
	s_cbranch_vccz .LBB0_1786
	s_sleep 1
	global_load_dword v1, v0, s[6:7] sc1
	s_waitcnt vmcnt(0)
	v_cmp_gt_u32_e32 vcc, 4, v1
	s_cbranch_vccz .LBB0_1786
	s_sleep 1
	global_load_dword v1, v0, s[6:7] sc1
	s_waitcnt vmcnt(0)
	v_cmp_gt_u32_e32 vcc, 4, v1
	s_cbranch_vccz .LBB0_1786
	s_add_i32 s2, s2, -5
	s_cmp_eq_u32 s2, 0
	s_cselect_b64 s[8:9], -1, 0
	s_sleep 1
	s_branch .LBB0_1786
.LBB0_1793:
	s_waitcnt vmcnt(0)
.LBB0_1794:
	s_or_b64 exec, exec, s[0:1]
	v_mov_b32_e32 v131, 0
	v_lshl_add_u64 v[0:1], v[136:137], 0, v[130:131]
	s_barrier
	global_load_dwordx4 v[182:185], v[0:1], off
	v_lshl_add_u64 v[0:1], v[128:129], 2, s[22:23]
	global_load_dwordx4 v[12:15], v[0:1], off
	global_load_dwordx4 v[8:11], v[0:1], off offset:16
	global_load_dwordx4 v[4:7], v[0:1], off offset:512
	s_nop 0
	global_load_dwordx4 v[0:3], v[0:1], off offset:528
	s_mov_b32 s2, 0xf800000
	v_lshl_add_u64 v[132:133], v[132:133], 2, s[24:25]
	s_waitcnt vmcnt(4)
	v_mov_b32_e32 v128, v183
	v_mov_b32_e32 v129, v184
	v_mov_b32_e32 v183, v185
	v_pk_add_f32 v[128:129], v[128:129], v[182:183]
	s_nop 0
	v_add_f32_e32 v128, v128, v129
	ds_bpermute_b32 v129, v181, v128
	s_waitcnt lgkmcnt(0)
	v_add_f32_e32 v129, v128, v129
	ds_bpermute_b32 v136, v180, v129
	v_mov_b32_e32 v128, 0x358637bd
	s_waitcnt lgkmcnt(0)
	v_add_f32_e32 v129, v129, v136
	v_fmamk_f32 v129, v129, 0x3a800000, v128
	v_mul_f32_e32 v136, 0x4f800000, v129
	v_cmp_gt_f32_e32 vcc, s2, v129
	s_nop 1
	v_cndmask_b32_e32 v136, v129, v136, vcc
	v_sqrt_f32_e32 v137, v136
	v_mov_b32_e32 v129, 0x260
	v_add_u32_e32 v182, -1, v137
	v_add_u32_e32 v183, 1, v137
	v_fma_f32 v184, -v182, v137, v136
	v_fma_f32 v185, -v183, v137, v136
	v_cmp_ge_f32_e64 s[0:1], 0, v184
	s_nop 1
	v_cndmask_b32_e64 v137, v137, v182, s[0:1]
	v_cmp_lt_f32_e64 s[0:1], 0, v185
	s_nop 1
	v_cndmask_b32_e64 v137, v137, v183, s[0:1]
	v_mul_f32_e32 v182, 0x37800000, v137
	v_cndmask_b32_e32 v137, v137, v182, vcc
	v_cmp_class_f32_e32 vcc, v136, v129
	s_nop 1
	v_cndmask_b32_e32 v182, v137, v136, vcc
	v_div_scale_f32 v183, s[0:1], v182, v182, 1.0
	v_rcp_f32_e32 v184, v183
	v_lshl_add_u64 v[136:137], v[142:143], 0, v[130:131]
	v_div_scale_f32 v142, vcc, 1.0, v182, 1.0
	v_fma_f32 v143, -v183, v184, 1.0
	v_fmac_f32_e32 v184, v143, v184
	v_mul_f32_e32 v143, v142, v184
	v_fma_f32 v185, -v183, v143, v142
	v_fmac_f32_e32 v143, v185, v184
	v_fma_f32 v142, -v183, v143, v142
	v_div_fmas_f32 v142, v142, v184, v143
	v_div_fixup_f32 v142, v142, v182, 1.0
	v_pk_mul_f32 v[122:123], v[122:123], v[142:143] op_sel_hi:[1,0]
	v_pk_mul_f32 v[126:127], v[126:127], v[142:143] op_sel_hi:[1,0]
	v_pk_mul_f32 v[120:121], v[120:121], v[142:143] op_sel_hi:[1,0]
	v_pk_mul_f32 v[124:125], v[124:125], v[142:143] op_sel_hi:[1,0]
	v_pk_mul_f32 v[182:183], v[112:113], v[142:143] op_sel_hi:[1,0]
	v_pk_mul_f32 v[184:185], v[114:115], v[142:143] op_sel_hi:[1,0]
	v_pk_mul_f32 v[186:187], v[116:117], v[142:143] op_sel_hi:[1,0]
	v_pk_mul_f32 v[142:143], v[118:119], v[142:143] op_sel_hi:[1,0]
	s_waitcnt vmcnt(3)
	v_pk_mul_f32 v[114:115], v[14:15], v[126:127]
	v_pk_mul_f32 v[112:113], v[12:13], v[122:123]
	s_waitcnt vmcnt(2)
	v_pk_mul_f32 v[118:119], v[10:11], v[124:125]
	v_pk_mul_f32 v[116:117], v[8:9], v[120:121]
	s_waitcnt vmcnt(1)
	v_pk_mul_f32 v[122:123], v[6:7], v[184:185]
	v_pk_mul_f32 v[120:121], v[4:5], v[182:183]
	s_waitcnt vmcnt(0)
	v_pk_mul_f32 v[126:127], v[2:3], v[142:143]
	v_pk_mul_f32 v[124:125], v[0:1], v[186:187]
	global_store_dwordx4 v[132:133], v[112:115], off
	global_store_dwordx4 v[132:133], v[116:119], off offset:16
	global_store_dwordx4 v[132:133], v[120:123], off offset:512
	global_store_dwordx4 v[132:133], v[124:127], off offset:528
	global_load_dwordx4 v[112:115], v[136:137], off
	s_waitcnt vmcnt(0)
	v_mov_b32_e32 v116, v113
	v_mov_b32_e32 v117, v114
	v_mov_b32_e32 v113, v115
	v_pk_add_f32 v[112:113], v[116:117], v[112:113]
	s_nop 0
	v_add_f32_e32 v112, v112, v113
	ds_bpermute_b32 v113, v181, v112
	s_waitcnt lgkmcnt(0)
	v_add_f32_e32 v112, v112, v113
	ds_bpermute_b32 v113, v180, v112
	s_waitcnt lgkmcnt(0)
	v_add_f32_e32 v112, v112, v113
	v_fmamk_f32 v112, v112, 0x3a800000, v128
	v_mul_f32_e32 v113, 0x4f800000, v112
	v_cmp_gt_f32_e32 vcc, s2, v112
	s_nop 1
	v_cndmask_b32_e32 v114, v112, v113, vcc
	v_sqrt_f32_e32 v115, v114
	v_lshl_add_u64 v[112:113], v[134:135], 2, s[24:25]
	v_add_u32_e32 v116, -1, v115
	v_add_u32_e32 v117, 1, v115
	v_fma_f32 v118, -v116, v115, v114
	v_fma_f32 v119, -v117, v115, v114
	v_cmp_ge_f32_e64 s[0:1], 0, v118
	s_nop 1
	v_cndmask_b32_e64 v115, v115, v116, s[0:1]
	v_cmp_lt_f32_e64 s[0:1], 0, v119
	s_nop 1
	v_cndmask_b32_e64 v115, v115, v117, s[0:1]
	v_mul_f32_e32 v116, 0x37800000, v115
	v_cndmask_b32_e32 v115, v115, v116, vcc
	v_cmp_class_f32_e32 vcc, v114, v129
	s_nop 1
	v_cndmask_b32_e32 v116, v115, v114, vcc
	v_div_scale_f32 v117, s[0:1], v116, v116, 1.0
	v_rcp_f32_e32 v118, v117
	v_div_scale_f32 v119, vcc, 1.0, v116, 1.0
	v_lshl_add_u64 v[114:115], v[146:147], 0, v[130:131]
	v_fma_f32 v120, -v117, v118, 1.0
	v_fmac_f32_e32 v118, v120, v118
	v_mul_f32_e32 v120, v119, v118
	v_fma_f32 v121, -v117, v120, v119
	v_fmac_f32_e32 v120, v121, v118
	v_fma_f32 v117, -v117, v120, v119
	v_div_fmas_f32 v117, v117, v118, v120
	v_div_fixup_f32 v116, v117, v116, 1.0
	v_pk_mul_f32 v[100:101], v[100:101], v[116:117] op_sel_hi:[1,0]
	v_pk_mul_f32 v[106:107], v[106:107], v[116:117] op_sel_hi:[1,0]
	v_pk_mul_f32 v[118:119], v[96:97], v[116:117] op_sel_hi:[1,0]
	v_pk_mul_f32 v[104:105], v[104:105], v[116:117] op_sel_hi:[1,0]
	v_pk_mul_f32 v[108:109], v[108:109], v[116:117] op_sel_hi:[1,0]
	v_pk_mul_f32 v[120:121], v[98:99], v[116:117] op_sel_hi:[1,0]
	v_pk_mul_f32 v[122:123], v[110:111], v[116:117] op_sel_hi:[1,0]
	v_pk_mul_f32 v[110:111], v[102:103], v[116:117] op_sel_hi:[1,0]
	v_pk_mul_f32 v[98:99], v[14:15], v[106:107]
	v_pk_mul_f32 v[96:97], v[12:13], v[100:101]
	v_pk_mul_f32 v[102:103], v[10:11], v[104:105]
	v_pk_mul_f32 v[100:101], v[8:9], v[118:119]
	v_pk_mul_f32 v[106:107], v[6:7], v[120:121]
	v_pk_mul_f32 v[104:105], v[4:5], v[108:109]
	v_pk_mul_f32 v[110:111], v[2:3], v[110:111]
	v_pk_mul_f32 v[108:109], v[0:1], v[122:123]
	global_store_dwordx4 v[112:113], v[96:99], off
	global_store_dwordx4 v[112:113], v[100:103], off offset:16
	global_store_dwordx4 v[112:113], v[104:107], off offset:512
	global_store_dwordx4 v[112:113], v[108:111], off offset:528
	global_load_dwordx4 v[96:99], v[114:115], off
	s_waitcnt vmcnt(0)
;     __device__ __forceinline__ void fused(const f32x4 (&acc_)[2][2][4][2], const Unit& u, int wr, int wc, int fr, int fq, LAS unsigned char*, int, int) const {
;     ...
;         for (int ai = 0; ai < 2; ++ai)
; #pragma unroll
;             for (int m = 0; m < 4; ++m) {
;                 const int row = row0 + ai * 128 + m * 16; const float rs = row_rstd_q(ssq, row, fq);
; #pragma unroll
;                 for (int bj = 0; bj < 2; ++bj) {
;                     const size_t off = (size_t)row * D_ + col0 + bj * 128;
;                     *(f32x4*)(out + off) = acc[ai][bj][m][0] * rs * g0[bj]; *(f32x4*)(out + off + 4) = acc[ai][bj][m][1] * rs * g1[bj];
;                 }
;             }
	v_mov_b32_e32 v100, v97
	v_mov_b32_e32 v101, v98
	v_mov_b32_e32 v97, v99
	v_pk_add_f32 v[96:97], v[100:101], v[96:97]
	s_nop 0
	v_add_f32_e32 v96, v96, v97
	ds_bpermute_b32 v97, v181, v96
	s_waitcnt lgkmcnt(0)
	v_add_f32_e32 v96, v96, v97
	ds_bpermute_b32 v97, v180, v96
	s_waitcnt lgkmcnt(0)
	v_add_f32_e32 v96, v96, v97
	v_fmamk_f32 v96, v96, 0x3a800000, v128
	v_mul_f32_e32 v97, 0x4f800000, v96
	v_cmp_gt_f32_e32 vcc, s2, v96
	s_nop 1
	v_cndmask_b32_e32 v98, v96, v97, vcc
	v_sqrt_f32_e32 v99, v98
	v_lshl_add_u64 v[96:97], v[140:141], 2, s[24:25]
	v_add_u32_e32 v100, -1, v99
	v_add_u32_e32 v101, 1, v99
	v_fma_f32 v102, -v100, v99, v98
	v_fma_f32 v103, -v101, v99, v98
	v_cmp_ge_f32_e64 s[0:1], 0, v102
	s_nop 1
	v_cndmask_b32_e64 v99, v99, v100, s[0:1]
	v_cmp_lt_f32_e64 s[0:1], 0, v103
	s_nop 1
	v_cndmask_b32_e64 v99, v99, v101, s[0:1]
	v_mul_f32_e32 v100, 0x37800000, v99
	v_cndmask_b32_e32 v99, v99, v100, vcc
	v_cmp_class_f32_e32 vcc, v98, v129
	s_nop 1
	v_cndmask_b32_e32 v100, v99, v98, vcc
	v_div_scale_f32 v101, s[0:1], v100, v100, 1.0
	v_rcp_f32_e32 v102, v101
	v_div_scale_f32 v103, vcc, 1.0, v100, 1.0
	v_lshl_add_u64 v[98:99], v[150:151], 0, v[130:131]
	v_fma_f32 v104, -v101, v102, 1.0
	v_fmac_f32_e32 v102, v104, v102
	v_mul_f32_e32 v104, v103, v102
	v_fma_f32 v105, -v101, v104, v103
	v_fmac_f32_e32 v104, v105, v102
	v_fma_f32 v101, -v101, v104, v103
	v_div_fmas_f32 v101, v101, v102, v104
	v_div_fixup_f32 v100, v101, v100, 1.0
	v_pk_mul_f32 v[88:89], v[88:89], v[100:101] op_sel_hi:[1,0]
	v_pk_mul_f32 v[92:93], v[92:93], v[100:101] op_sel_hi:[1,0]
	v_pk_mul_f32 v[84:85], v[84:85], v[100:101] op_sel_hi:[1,0]
	v_pk_mul_f32 v[90:91], v[90:91], v[100:101] op_sel_hi:[1,0]
	v_pk_mul_f32 v[102:103], v[80:81], v[100:101] op_sel_hi:[1,0]
	v_pk_mul_f32 v[104:105], v[82:83], v[100:101] op_sel_hi:[1,0]
	v_pk_mul_f32 v[106:107], v[94:95], v[100:101] op_sel_hi:[1,0]
	v_pk_mul_f32 v[94:95], v[86:87], v[100:101] op_sel_hi:[1,0]
	v_pk_mul_f32 v[82:83], v[14:15], v[92:93]
	v_pk_mul_f32 v[80:81], v[12:13], v[88:89]
	v_pk_mul_f32 v[86:87], v[10:11], v[90:91]
	v_pk_mul_f32 v[84:85], v[8:9], v[84:85]
	v_pk_mul_f32 v[90:91], v[6:7], v[104:105]
	v_pk_mul_f32 v[88:89], v[4:5], v[102:103]
	v_pk_mul_f32 v[94:95], v[2:3], v[94:95]
	v_pk_mul_f32 v[92:93], v[0:1], v[106:107]
	global_store_dwordx4 v[96:97], v[80:83], off
	global_store_dwordx4 v[96:97], v[84:87], off offset:16
	global_store_dwordx4 v[96:97], v[88:91], off offset:512
	global_store_dwordx4 v[96:97], v[92:95], off offset:528
	global_load_dwordx4 v[80:83], v[98:99], off
	s_waitcnt vmcnt(0)
	v_mov_b32_e32 v84, v81
	v_mov_b32_e32 v85, v82
	v_mov_b32_e32 v81, v83
	v_pk_add_f32 v[80:81], v[84:85], v[80:81]
	s_nop 0
	v_add_f32_e32 v80, v80, v81
	ds_bpermute_b32 v81, v181, v80
	s_waitcnt lgkmcnt(0)
	v_add_f32_e32 v80, v80, v81
	ds_bpermute_b32 v81, v180, v80
	s_waitcnt lgkmcnt(0)
	v_add_f32_e32 v80, v80, v81
	v_fmamk_f32 v80, v80, 0x3a800000, v128
	v_mul_f32_e32 v81, 0x4f800000, v80
	v_cmp_gt_f32_e32 vcc, s2, v80
	s_nop 1
	v_cndmask_b32_e32 v82, v80, v81, vcc
	v_sqrt_f32_e32 v83, v82
	v_lshl_add_u64 v[80:81], v[144:145], 2, s[24:25]
	v_add_u32_e32 v84, -1, v83
	v_add_u32_e32 v85, 1, v83
	v_fma_f32 v86, -v84, v83, v82
	v_fma_f32 v87, -v85, v83, v82
	v_cmp_ge_f32_e64 s[0:1], 0, v86
	s_nop 1
	v_cndmask_b32_e64 v83, v83, v84, s[0:1]
	v_cmp_lt_f32_e64 s[0:1], 0, v87
	s_nop 1
	v_cndmask_b32_e64 v83, v83, v85, s[0:1]
	v_mul_f32_e32 v84, 0x37800000, v83
	v_cndmask_b32_e32 v83, v83, v84, vcc
	v_cmp_class_f32_e32 vcc, v82, v129
	s_nop 1
	v_cndmask_b32_e32 v84, v83, v82, vcc
	v_div_scale_f32 v85, s[0:1], v84, v84, 1.0
	v_rcp_f32_e32 v86, v85
	v_div_scale_f32 v87, vcc, 1.0, v84, 1.0
	v_lshl_add_u64 v[82:83], v[154:155], 0, v[130:131]
	v_fma_f32 v88, -v85, v86, 1.0
	v_fmac_f32_e32 v86, v88, v86
	v_mul_f32_e32 v88, v87, v86
	v_fma_f32 v89, -v85, v88, v87
	v_fmac_f32_e32 v88, v89, v86
	v_fma_f32 v85, -v85, v88, v87
	v_div_fmas_f32 v85, v85, v86, v88
	v_div_fixup_f32 v84, v85, v84, 1.0
	v_pk_mul_f32 v[68:69], v[68:69], v[84:85] op_sel_hi:[1,0]
	v_pk_mul_f32 v[74:75], v[74:75], v[84:85] op_sel_hi:[1,0]
	v_pk_mul_f32 v[86:87], v[64:65], v[84:85] op_sel_hi:[1,0]
	v_pk_mul_f32 v[72:73], v[72:73], v[84:85] op_sel_hi:[1,0]
	v_pk_mul_f32 v[76:77], v[76:77], v[84:85] op_sel_hi:[1,0]
	v_pk_mul_f32 v[88:89], v[66:67], v[84:85] op_sel_hi:[1,0]
	v_pk_mul_f32 v[90:91], v[78:79], v[84:85] op_sel_hi:[1,0]
	v_pk_mul_f32 v[78:79], v[70:71], v[84:85] op_sel_hi:[1,0]
	v_pk_mul_f32 v[66:67], v[14:15], v[74:75]
	v_pk_mul_f32 v[64:65], v[12:13], v[68:69]
	v_pk_mul_f32 v[70:71], v[10:11], v[72:73]
	v_pk_mul_f32 v[68:69], v[8:9], v[86:87]
	v_pk_mul_f32 v[74:75], v[6:7], v[88:89]
	v_pk_mul_f32 v[72:73], v[4:5], v[76:77]
	v_pk_mul_f32 v[78:79], v[2:3], v[78:79]
	v_pk_mul_f32 v[76:77], v[0:1], v[90:91]
	global_store_dwordx4 v[80:81], v[64:67], off
	global_store_dwordx4 v[80:81], v[68:71], off offset:16
	global_store_dwordx4 v[80:81], v[72:75], off offset:512
	global_store_dwordx4 v[80:81], v[76:79], off offset:528
	global_load_dwordx4 v[64:67], v[82:83], off
	s_waitcnt vmcnt(0)
	v_mov_b32_e32 v68, v65
	v_mov_b32_e32 v69, v66
	v_mov_b32_e32 v65, v67
	v_pk_add_f32 v[64:65], v[68:69], v[64:65]
	s_nop 0
	v_add_f32_e32 v64, v64, v65
	ds_bpermute_b32 v65, v181, v64
	s_waitcnt lgkmcnt(0)
	v_add_f32_e32 v64, v64, v65
	ds_bpermute_b32 v65, v180, v64
	s_waitcnt lgkmcnt(0)
;     __device__ __forceinline__ void fused(const f32x4 (&acc_)[2][2][4][2], const Unit& u, int wr, int wc, int fr, int fq, LAS unsigned char*, int, int) const {
;     ...
;         for (int ai = 0; ai < 2; ++ai)
; #pragma unroll
;             for (int m = 0; m < 4; ++m) {
;                 const int row = row0 + ai * 128 + m * 16; const float rs = row_rstd_q(ssq, row, fq);
; #pragma unroll
;                 for (int bj = 0; bj < 2; ++bj) {
;                     const size_t off = (size_t)row * D_ + col0 + bj * 128;
;                     *(f32x4*)(out + off) = acc[ai][bj][m][0] * rs * g0[bj]; *(f32x4*)(out + off + 4) = acc[ai][bj][m][1] * rs * g1[bj];
;                 }
;             }
	v_add_f32_e32 v64, v64, v65
	v_fmamk_f32 v64, v64, 0x3a800000, v128
	v_mul_f32_e32 v65, 0x4f800000, v64
	v_cmp_gt_f32_e32 vcc, s2, v64
	s_nop 1
	v_cndmask_b32_e32 v66, v64, v65, vcc
	v_sqrt_f32_e32 v67, v66
	v_lshl_add_u64 v[64:65], v[148:149], 2, s[24:25]
	v_add_u32_e32 v68, -1, v67
	v_add_u32_e32 v69, 1, v67
	v_fma_f32 v70, -v68, v67, v66
	v_fma_f32 v71, -v69, v67, v66
	v_cmp_ge_f32_e64 s[0:1], 0, v70
	s_nop 1
	v_cndmask_b32_e64 v67, v67, v68, s[0:1]
	v_cmp_lt_f32_e64 s[0:1], 0, v71
	s_nop 1
	v_cndmask_b32_e64 v67, v67, v69, s[0:1]
	v_mul_f32_e32 v68, 0x37800000, v67
	v_cndmask_b32_e32 v67, v67, v68, vcc
	v_cmp_class_f32_e32 vcc, v66, v129
	s_nop 1
	v_cndmask_b32_e32 v68, v67, v66, vcc
	v_div_scale_f32 v69, s[0:1], v68, v68, 1.0
	v_rcp_f32_e32 v70, v69
	v_div_scale_f32 v71, vcc, 1.0, v68, 1.0
	v_lshl_add_u64 v[66:67], v[158:159], 0, v[130:131]
	v_fma_f32 v72, -v69, v70, 1.0
	v_fmac_f32_e32 v70, v72, v70
	v_mul_f32_e32 v72, v71, v70
	v_fma_f32 v73, -v69, v72, v71
	v_fmac_f32_e32 v72, v73, v70
	v_fma_f32 v69, -v69, v72, v71
	v_div_fmas_f32 v69, v69, v70, v72
	v_div_fixup_f32 v68, v69, v68, 1.0
	v_pk_mul_f32 v[56:57], v[56:57], v[68:69] op_sel_hi:[1,0]
	v_pk_mul_f32 v[60:61], v[60:61], v[68:69] op_sel_hi:[1,0]
	v_pk_mul_f32 v[52:53], v[52:53], v[68:69] op_sel_hi:[1,0]
	v_pk_mul_f32 v[58:59], v[58:59], v[68:69] op_sel_hi:[1,0]
	v_pk_mul_f32 v[70:71], v[48:49], v[68:69] op_sel_hi:[1,0]
	v_pk_mul_f32 v[72:73], v[50:51], v[68:69] op_sel_hi:[1,0]
	v_pk_mul_f32 v[74:75], v[62:63], v[68:69] op_sel_hi:[1,0]
	v_pk_mul_f32 v[62:63], v[54:55], v[68:69] op_sel_hi:[1,0]
	v_pk_mul_f32 v[50:51], v[14:15], v[60:61]
	v_pk_mul_f32 v[48:49], v[12:13], v[56:57]
	v_pk_mul_f32 v[54:55], v[10:11], v[58:59]
	v_pk_mul_f32 v[52:53], v[8:9], v[52:53]
	v_pk_mul_f32 v[58:59], v[6:7], v[72:73]
	v_pk_mul_f32 v[56:57], v[4:5], v[70:71]
	v_pk_mul_f32 v[62:63], v[2:3], v[62:63]
	v_pk_mul_f32 v[60:61], v[0:1], v[74:75]
	global_store_dwordx4 v[64:65], v[48:51], off
	global_store_dwordx4 v[64:65], v[52:55], off offset:16
	global_store_dwordx4 v[64:65], v[56:59], off offset:512
	global_store_dwordx4 v[64:65], v[60:63], off offset:528
	global_load_dwordx4 v[48:51], v[66:67], off
	s_waitcnt vmcnt(0)
	v_mov_b32_e32 v52, v49
	v_mov_b32_e32 v53, v50
	v_mov_b32_e32 v49, v51
	v_pk_add_f32 v[48:49], v[52:53], v[48:49]
	s_nop 0
	v_add_f32_e32 v48, v48, v49
	ds_bpermute_b32 v49, v181, v48
	s_waitcnt lgkmcnt(0)
	v_add_f32_e32 v48, v48, v49
	ds_bpermute_b32 v49, v180, v48
	s_waitcnt lgkmcnt(0)
	v_add_f32_e32 v48, v48, v49
	v_fmamk_f32 v48, v48, 0x3a800000, v128
	v_mul_f32_e32 v49, 0x4f800000, v48
	v_cmp_gt_f32_e32 vcc, s2, v48
	s_nop 1
	v_cndmask_b32_e32 v50, v48, v49, vcc
	v_sqrt_f32_e32 v51, v50
	v_lshl_add_u64 v[48:49], v[152:153], 2, s[24:25]
	v_add_u32_e32 v52, -1, v51
	v_add_u32_e32 v53, 1, v51
	v_fma_f32 v54, -v52, v51, v50
	v_fma_f32 v55, -v53, v51, v50
	v_cmp_ge_f32_e64 s[0:1], 0, v54
	s_nop 1
	v_cndmask_b32_e64 v51, v51, v52, s[0:1]
	v_cmp_lt_f32_e64 s[0:1], 0, v55
	s_nop 1
	v_cndmask_b32_e64 v51, v51, v53, s[0:1]
	v_mul_f32_e32 v52, 0x37800000, v51
	v_cndmask_b32_e32 v51, v51, v52, vcc
	v_cmp_class_f32_e32 vcc, v50, v129
	s_nop 1
	v_cndmask_b32_e32 v52, v51, v50, vcc
	v_div_scale_f32 v53, s[0:1], v52, v52, 1.0
	v_rcp_f32_e32 v54, v53
	v_div_scale_f32 v55, vcc, 1.0, v52, 1.0
	v_lshl_add_u64 v[50:51], v[160:161], 0, v[130:131]
	v_fma_f32 v56, -v53, v54, 1.0
	v_fmac_f32_e32 v54, v56, v54
	v_mul_f32_e32 v56, v55, v54
	v_fma_f32 v57, -v53, v56, v55
	v_fmac_f32_e32 v56, v57, v54
	v_fma_f32 v53, -v53, v56, v55
	v_div_fmas_f32 v53, v53, v54, v56
	v_div_fixup_f32 v52, v53, v52, 1.0
	v_pk_mul_f32 v[36:37], v[36:37], v[52:53] op_sel_hi:[1,0]
	v_pk_mul_f32 v[42:43], v[42:43], v[52:53] op_sel_hi:[1,0]
	v_pk_mul_f32 v[54:55], v[32:33], v[52:53] op_sel_hi:[1,0]
	v_pk_mul_f32 v[40:41], v[40:41], v[52:53] op_sel_hi:[1,0]
	v_pk_mul_f32 v[44:45], v[44:45], v[52:53] op_sel_hi:[1,0]
	v_pk_mul_f32 v[56:57], v[34:35], v[52:53] op_sel_hi:[1,0]
	v_pk_mul_f32 v[58:59], v[46:47], v[52:53] op_sel_hi:[1,0]
	v_pk_mul_f32 v[46:47], v[38:39], v[52:53] op_sel_hi:[1,0]
	v_pk_mul_f32 v[34:35], v[14:15], v[42:43]
	v_pk_mul_f32 v[32:33], v[12:13], v[36:37]
	v_pk_mul_f32 v[38:39], v[10:11], v[40:41]
	v_pk_mul_f32 v[36:37], v[8:9], v[54:55]
	v_pk_mul_f32 v[42:43], v[6:7], v[56:57]
	v_pk_mul_f32 v[40:41], v[4:5], v[44:45]
	v_pk_mul_f32 v[46:47], v[2:3], v[46:47]
	v_pk_mul_f32 v[44:45], v[0:1], v[58:59]
	global_store_dwordx4 v[48:49], v[32:35], off
	global_store_dwordx4 v[48:49], v[36:39], off offset:16
	global_store_dwordx4 v[48:49], v[40:43], off offset:512
	global_store_dwordx4 v[48:49], v[44:47], off offset:528
	global_load_dwordx4 v[32:35], v[50:51], off
	s_waitcnt vmcnt(0)
;     __device__ __forceinline__ void fused(const f32x4 (&acc_)[2][2][4][2], const Unit& u, int wr, int wc, int fr, int fq, LAS unsigned char*, int, int) const {
;     ...
;         for (int ai = 0; ai < 2; ++ai)
; #pragma unroll
;             for (int m = 0; m < 4; ++m) {
;                 const int row = row0 + ai * 128 + m * 16; const float rs = row_rstd_q(ssq, row, fq);
; #pragma unroll
;                 for (int bj = 0; bj < 2; ++bj) {
;                     const size_t off = (size_t)row * D_ + col0 + bj * 128;
;                     *(f32x4*)(out + off) = acc[ai][bj][m][0] * rs * g0[bj]; *(f32x4*)(out + off + 4) = acc[ai][bj][m][1] * rs * g1[bj];
;                 }
;             }
	v_mov_b32_e32 v36, v33
	v_mov_b32_e32 v37, v34
	v_mov_b32_e32 v33, v35
	v_pk_add_f32 v[32:33], v[36:37], v[32:33]
	s_nop 0
	v_add_f32_e32 v32, v32, v33
	ds_bpermute_b32 v33, v181, v32
	s_waitcnt lgkmcnt(0)
	v_add_f32_e32 v32, v32, v33
	ds_bpermute_b32 v33, v180, v32
	s_waitcnt lgkmcnt(0)
	v_add_f32_e32 v32, v32, v33
	v_fmamk_f32 v32, v32, 0x3a800000, v128
	v_mul_f32_e32 v33, 0x4f800000, v32
	v_cmp_gt_f32_e32 vcc, s2, v32
	s_nop 1
	v_cndmask_b32_e32 v34, v32, v33, vcc
	v_sqrt_f32_e32 v35, v34
	v_lshl_add_u64 v[32:33], v[156:157], 2, s[24:25]
	v_add_u32_e32 v36, -1, v35
	v_add_u32_e32 v37, 1, v35
	v_fma_f32 v38, -v36, v35, v34
	v_fma_f32 v39, -v37, v35, v34
	v_cmp_ge_f32_e64 s[0:1], 0, v38
	s_nop 1
	v_cndmask_b32_e64 v35, v35, v36, s[0:1]
	v_cmp_lt_f32_e64 s[0:1], 0, v39
	s_nop 1
	v_cndmask_b32_e64 v35, v35, v37, s[0:1]
	v_mul_f32_e32 v36, 0x37800000, v35
	v_cndmask_b32_e32 v35, v35, v36, vcc
	v_cmp_class_f32_e32 vcc, v34, v129
	s_nop 1
	v_cndmask_b32_e32 v36, v35, v34, vcc
	v_div_scale_f32 v37, s[0:1], v36, v36, 1.0
	v_rcp_f32_e32 v38, v37
	v_div_scale_f32 v39, vcc, 1.0, v36, 1.0
	v_lshl_add_u64 v[34:35], v[178:179], 0, v[130:131]
	v_fma_f32 v40, -v37, v38, 1.0
	v_fmac_f32_e32 v38, v40, v38
	v_mul_f32_e32 v40, v39, v38
	v_fma_f32 v41, -v37, v40, v39
	v_fmac_f32_e32 v40, v41, v38
	v_fma_f32 v37, -v37, v40, v39
	v_div_fmas_f32 v37, v37, v38, v40
	v_div_fixup_f32 v36, v37, v36, 1.0
	v_pk_mul_f32 v[24:25], v[24:25], v[36:37] op_sel_hi:[1,0]
	v_pk_mul_f32 v[28:29], v[28:29], v[36:37] op_sel_hi:[1,0]
	v_pk_mul_f32 v[20:21], v[20:21], v[36:37] op_sel_hi:[1,0]
	v_pk_mul_f32 v[26:27], v[26:27], v[36:37] op_sel_hi:[1,0]
	v_pk_mul_f32 v[38:39], v[16:17], v[36:37] op_sel_hi:[1,0]
	v_pk_mul_f32 v[40:41], v[18:19], v[36:37] op_sel_hi:[1,0]
	v_pk_mul_f32 v[42:43], v[30:31], v[36:37] op_sel_hi:[1,0]
	v_pk_mul_f32 v[30:31], v[22:23], v[36:37] op_sel_hi:[1,0]
	v_pk_mul_f32 v[18:19], v[14:15], v[28:29]
	v_pk_mul_f32 v[16:17], v[12:13], v[24:25]
	v_pk_mul_f32 v[22:23], v[10:11], v[26:27]
	v_pk_mul_f32 v[20:21], v[8:9], v[20:21]
	v_pk_mul_f32 v[26:27], v[6:7], v[40:41]
	v_pk_mul_f32 v[24:25], v[4:5], v[38:39]
	v_pk_mul_f32 v[30:31], v[2:3], v[30:31]
	v_pk_mul_f32 v[28:29], v[0:1], v[42:43]
	global_store_dwordx4 v[32:33], v[16:19], off
	global_store_dwordx4 v[32:33], v[20:23], off offset:16
	global_store_dwordx4 v[32:33], v[24:27], off offset:512
	global_store_dwordx4 v[32:33], v[28:31], off offset:528
	global_load_dwordx4 v[16:19], v[34:35], off
	s_waitcnt vmcnt(0)
	v_mov_b32_e32 v20, v17
	v_mov_b32_e32 v21, v18
	v_mov_b32_e32 v17, v19
	v_pk_add_f32 v[16:17], v[20:21], v[16:17]
	s_nop 0
	v_add_f32_e32 v16, v16, v17
	ds_bpermute_b32 v17, v181, v16
	s_waitcnt lgkmcnt(0)
	v_add_f32_e32 v16, v16, v17
	ds_bpermute_b32 v17, v180, v16
	s_waitcnt lgkmcnt(0)
	v_add_f32_e32 v16, v16, v17
	v_fmac_f32_e32 v128, 0x3a800000, v16
	v_mul_f32_e32 v16, 0x4f800000, v128
	v_cmp_gt_f32_e32 vcc, s2, v128
	s_nop 1
	v_cndmask_b32_e32 v16, v128, v16, vcc
	v_sqrt_f32_e32 v17, v16
	s_nop 0
	v_add_u32_e32 v18, -1, v17
	v_add_u32_e32 v19, 1, v17
	v_fma_f32 v20, -v18, v17, v16
	v_fma_f32 v21, -v19, v17, v16
	v_cmp_ge_f32_e64 s[0:1], 0, v20
	s_nop 1
	v_cndmask_b32_e64 v17, v17, v18, s[0:1]
	v_cmp_lt_f32_e64 s[0:1], 0, v21
	s_nop 1
	v_cndmask_b32_e64 v17, v17, v19, s[0:1]
	v_mul_f32_e32 v18, 0x37800000, v17
	v_cndmask_b32_e32 v17, v17, v18, vcc
	v_cmp_class_f32_e32 vcc, v16, v129
	s_nop 1
	v_cndmask_b32_e32 v18, v17, v16, vcc
	v_div_scale_f32 v19, s[0:1], v18, v18, 1.0
	v_rcp_f32_e32 v20, v19
	v_div_scale_f32 v21, vcc, 1.0, v18, 1.0
	v_lshl_add_u64 v[16:17], v[138:139], 2, s[24:25]
	v_fma_f32 v22, -v19, v20, 1.0
	v_fmac_f32_e32 v20, v22, v20
	v_mul_f32_e32 v22, v21, v20
	v_fma_f32 v23, -v19, v22, v21
	v_fmac_f32_e32 v22, v23, v20
	v_fma_f32 v19, -v19, v22, v21
	v_div_fmas_f32 v19, v19, v20, v22
	v_div_fixup_f32 v18, v19, v18, 1.0
	v_pk_mul_f32 v[20:21], v[168:169], v[18:19] op_sel_hi:[1,0]
	v_pk_mul_f32 v[22:23], v[170:171], v[18:19] op_sel_hi:[1,0]
	v_pk_mul_f32 v[24:25], v[162:163], v[18:19] op_sel_hi:[1,0]
	v_pk_mul_f32 v[26:27], v[166:167], v[18:19] op_sel_hi:[1,0]
	v_pk_mul_f32 v[28:29], v[164:165], v[18:19] op_sel_hi:[1,0]
	v_pk_mul_f32 v[30:31], v[174:175], v[18:19] op_sel_hi:[1,0]
	v_pk_mul_f32 v[32:33], v[172:173], v[18:19] op_sel_hi:[1,0]
	v_pk_mul_f32 v[18:19], v[176:177], v[18:19] op_sel_hi:[1,0]
	v_pk_mul_f32 v[14:15], v[14:15], v[22:23]
	v_pk_mul_f32 v[12:13], v[12:13], v[20:21]
	v_pk_mul_f32 v[10:11], v[10:11], v[26:27]
	v_pk_mul_f32 v[8:9], v[8:9], v[24:25]
	v_pk_mul_f32 v[6:7], v[6:7], v[30:31]
	v_pk_mul_f32 v[4:5], v[4:5], v[28:29]
	v_pk_mul_f32 v[2:3], v[2:3], v[18:19]
	v_pk_mul_f32 v[0:1], v[0:1], v[32:33]
	global_store_dwordx4 v[16:17], v[12:15], off
	global_store_dwordx4 v[16:17], v[8:11], off offset:16
	global_store_dwordx4 v[16:17], v[4:7], off offset:512
	global_store_dwordx4 v[16:17], v[0:3], off offset:528

; __device__ __forceinline__ unsigned xb_ld(unsigned* p)              { return __hip_atomic_load(p, __ATOMIC_RELAXED, __HIP_MEMORY_SCOPE_AGENT); }
; __device__ __forceinline__ unsigned xb_add(unsigned* p, unsigned v) { return __hip_atomic_fetch_add(p, v, __ATOMIC_RELAXED, __HIP_MEMORY_SCOPE_AGENT); }
; #define XB_SPIN(cond, bar) do { unsigned _sp = 0; while (cond) { __builtin_amdgcn_s_sleep(1); \
;     if ((++_sp & 255u) == 0u) { if (xb_ld(&(bar)[XB_TMO])) break; if (_sp > XB_SPIN_CAP) { atomicAdd(&(bar)[XB_TMO], 1u); break; } } } } while (0)
; __device__ __forceinline__ void xcd_barrier(const XcdBarrier& b) {
;     ...
;         const unsigned old = xb_add(&bar[XB_XSUB(b.x)], 1u);
;         const unsigned gen = old / nloc;
;         if (old + 1u == (gen + 1u) * nloc) {
;             __builtin_amdgcn_fence(__ATOMIC_RELEASE, "agent");
;             asm volatile("s_waitcnt vmcnt(0)" ::: "memory");
;             const unsigned og = xb_add(&bar[XB_TOP], 1u);
;             const unsigned tg = og / nx;
;             if (og + 1u == (tg + 1u) * nx) xb_add(&bar[XB_TOPGEN], 1u);
;             else XB_SPIN(xb_ld(&bar[XB_TOPGEN]) == tg, bar);
;             __builtin_amdgcn_fence(__ATOMIC_ACQUIRE, "agent");
;             xb_add(&bar[XB_XGEN(b.x)], 1u);
;             asm volatile("s_waitcnt vmcnt(0)" ::: "memory");
;         } else {
;             XB_SPIN(xb_ld(&bar[XB_XGEN(b.x)]) == gen, bar);
;             __builtin_amdgcn_fence(__ATOMIC_ACQUIRE, "agent");
.LBB0_1814:
	s_or_b64 exec, exec, s[10:11]
	v_cvt_f32_u32_e32 v4, v2
	s_waitcnt vmcnt(0)
	v_readfirstlane_b32 s2, v3
	v_sub_u32_e32 v3, 0, v2
	v_rcp_iflag_f32_e32 v4, v4
	v_add_u32_e32 v5, s2, v1
	v_mul_f32_e32 v4, 0x4f7ffffe, v4
	v_cvt_u32_f32_e32 v4, v4
	v_mul_lo_u32 v1, v3, v4
	v_mul_hi_u32 v1, v4, v1
	v_add_u32_e32 v1, v4, v1
	v_mul_hi_u32 v1, v5, v1
	v_mul_lo_u32 v3, v1, v2
	v_sub_u32_e32 v3, v5, v3
	v_add_u32_e32 v4, 1, v1
	v_cmp_ge_u32_e32 vcc, v3, v2
	s_nop 1
	v_cndmask_b32_e32 v1, v1, v4, vcc
	v_sub_u32_e32 v4, v3, v2
	v_cndmask_b32_e32 v3, v3, v4, vcc
	v_add_u32_e32 v4, 1, v1
	v_cmp_ge_u32_e32 vcc, v3, v2
	v_add_u32_e32 v3, 1, v5
	s_nop 0
	v_cndmask_b32_e32 v1, v1, v4, vcc
	v_mul_lo_u32 v4, v2, v1
	v_add_u32_e32 v2, v4, v2
	v_cmp_ne_u32_e32 vcc, v3, v2
	s_and_saveexec_b64 s[2:3], vcc
	s_xor_b64 s[8:9], exec, s[2:3]
	s_cbranch_execz .LBB0_1828
	s_waitcnt lgkmcnt(0)
	buffer_inv sc1
	s_add_u32 s16, s26, 0xff03500
	s_addc_u32 s17, s27, 0
	v_mov_b32_e32 v0, 0
	global_load_dword v0, v0, s[16:17] sc1
	s_waitcnt vmcnt(0)
	v_cmp_eq_u32_e32 vcc, v0, v1
	s_and_saveexec_b64 s[10:11], vcc
	s_cbranch_execz .LBB0_1827
	s_add_u32 s14, s26, 0xff00200
	s_addc_u32 s15, s27, 0
	s_mov_b32 s2, 1
	s_mov_b64 s[18:19], 0
	v_mov_b32_e32 v0, 0
	s_branch .LBB0_1818

; __device__ __forceinline__ unsigned xb_ld(unsigned* p)              { return __hip_atomic_load(p, __ATOMIC_RELAXED, __HIP_MEMORY_SCOPE_AGENT); }
; __device__ __forceinline__ unsigned xb_add(unsigned* p, unsigned v) { return __hip_atomic_fetch_add(p, v, __ATOMIC_RELAXED, __HIP_MEMORY_SCOPE_AGENT); }
; #define XB_SPIN(cond, bar) do { unsigned _sp = 0; while (cond) { __builtin_amdgcn_s_sleep(1); \
;     if ((++_sp & 255u) == 0u) { if (xb_ld(&(bar)[XB_TMO])) break; if (_sp > XB_SPIN_CAP) { atomicAdd(&(bar)[XB_TMO], 1u); break; } } } } while (0)
; __device__ __forceinline__ void xcd_barrier(const XcdBarrier& b) {
;     ...
;             if (og + 1u == (tg + 1u) * nx) xb_add(&bar[XB_TOPGEN], 1u);
;             else XB_SPIN(xb_ld(&bar[XB_TOPGEN]) == tg, bar);
;             __builtin_amdgcn_fence(__ATOMIC_ACQUIRE, "agent");
;             xb_add(&bar[XB_XGEN(b.x)], 1u);
;             asm volatile("s_waitcnt vmcnt(0)" ::: "memory");
.LBB0_1845:
	s_or_b64 exec, exec, s[8:9]
	s_mov_b64 s[8:9], exec
	v_mbcnt_lo_u32_b32 v0, s8, 0
	v_mbcnt_hi_u32_b32 v0, s9, v0
	v_cmp_eq_u32_e32 vcc, 0, v0
	s_waitcnt vmcnt(0)
	s_and_saveexec_b64 s[10:11], vcc
	s_cbranch_execz .LBB0_1847
	s_bcnt1_i32_b64 s2, s[8:9]
	v_mov_b32_e32 v0, 0x2000
	v_mov_b32_e32 v1, s2
.LBB0_1847:
	s_or_b64 exec, exec, s[10:11]
	s_waitcnt vmcnt(0)
